# residual GEMM epilogue software-pipelined (counted vmcnt) on top of foldfix+attention
# baseline (speedup 1.0000x reference)
.LBB0_514:
	s_add_i32 vcc_hi, s2, 2
	s_add_u32 s21, s6, 0x80
	s_addc_u32 s3, s7, 0
	s_add_i32 s74, 0, 0x10000
	v_add_u32_e32 v140, s74, v161
	ds_read_b128 v[128:131], v140
	ds_read_b128 v[132:135], v140 offset:1024
	ds_read_b128 v[136:139], v140 offset:2048
	ds_read_b128 v[140:143], v140 offset:3072
	s_cmp_eq_u32 s82, s2
	s_cselect_b32 s2, s80, s21
	s_cselect_b32 s3, s81, s3
	s_cselect_b32 s61, s39, vcc_lo
	s_cselect_b32 s60, s38, s83
	v_lshl_add_u64 v[206:207], s[6:7], 0, v[168:169]
	s_add_i32 m0, s88, 0xc000
	ds_read_b128 v[144:147], v214
	ds_read_b128 v[148:151], v214 offset:1024
	ds_read_b128 v[152:155], v214 offset:2048
	ds_read_b128 v[170:173], v214 offset:3072
	ds_read_b128 v[174:177], v214 offset:4096
	ds_read_b128 v[178:181], v214 offset:5120
	ds_read_b128 v[182:185], v214 offset:6144
	ds_read_b128 v[186:189], v214 offset:7168
	global_load_lds_dwordx4 v[206:207], off
	v_lshl_add_u64 v[206:207], s[6:7], 0, v[166:167]
	s_add_i32 m0, s88, 0xe000
	s_nop 0
	global_load_lds_dwordx4 v[206:207], off
	s_waitcnt lgkmcnt(8)
	s_barrier
	s_waitcnt lgkmcnt(0)
	s_setprio 1
	s_waitcnt lgkmcnt(0)
	v_mfma_f32_16x16x32_bf16 v[124:127], v[128:131], v[144:147], v[124:127]
	v_mfma_f32_16x16x32_bf16 v[120:123], v[136:139], v[144:147], v[120:123]
	v_mfma_f32_16x16x32_bf16 v[116:119], v[128:131], v[152:155], v[116:119]
	v_mfma_f32_16x16x32_bf16 v[108:111], v[136:139], v[152:155], v[108:111]
	v_mfma_f32_16x16x32_bf16 v[100:103], v[128:131], v[174:177], v[100:103]
	v_mfma_f32_16x16x32_bf16 v[92:95], v[136:139], v[174:177], v[92:95]
	v_mfma_f32_16x16x32_bf16 v[84:87], v[128:131], v[182:185], v[84:87]
	v_mfma_f32_16x16x32_bf16 v[76:79], v[136:139], v[182:185], v[76:79]
	v_mfma_f32_16x16x32_bf16 v[124:127], v[132:135], v[148:151], v[124:127]
	v_mfma_f32_16x16x32_bf16 v[120:123], v[140:143], v[148:151], v[120:123]
	v_mfma_f32_16x16x32_bf16 v[116:119], v[132:135], v[170:173], v[116:119]
	v_mfma_f32_16x16x32_bf16 v[108:111], v[140:143], v[170:173], v[108:111]
	v_mfma_f32_16x16x32_bf16 v[100:103], v[132:135], v[178:181], v[100:103]
	v_mfma_f32_16x16x32_bf16 v[92:95], v[140:143], v[178:181], v[92:95]
	v_mfma_f32_16x16x32_bf16 v[84:87], v[132:135], v[186:189], v[84:87]
	v_mfma_f32_16x16x32_bf16 v[76:79], v[140:143], v[186:189], v[76:79]
	s_setprio 0
	s_barrier
	s_add_i32 s21, 0, 0x14000
	s_add_i32 s74, s74, s53
	v_add_u32_e32 v215, s21, v161
	v_lshl_add_u64 v[228:229], s[60:61], 0, v[156:157]
	s_mov_b32 m0, s74
	ds_read_b128 v[206:209], v215
	ds_read_b128 v[216:219], v215 offset:1024
	ds_read_b128 v[220:223], v215 offset:2048
	ds_read_b128 v[224:227], v215 offset:3072
	global_load_lds_dwordx4 v[228:229], off
	v_lshl_add_u64 v[230:231], s[60:61], 0, v[162:163]
	s_add_i32 m0, s74, 0x2000
	s_nop 0
	global_load_lds_dwordx4 v[230:231], off
	s_barrier
	s_waitcnt lgkmcnt(0)
	s_setprio 1
	s_waitcnt lgkmcnt(0)
	v_mfma_f32_16x16x32_bf16 v[112:115], v[206:209], v[144:147], v[112:115]
	v_mfma_f32_16x16x32_bf16 v[104:107], v[220:223], v[144:147], v[104:107]
	v_mfma_f32_16x16x32_bf16 v[96:99], v[206:209], v[152:155], v[96:99]
	v_mfma_f32_16x16x32_bf16 v[88:91], v[220:223], v[152:155], v[88:91]
	v_mfma_f32_16x16x32_bf16 v[80:83], v[206:209], v[174:177], v[80:83]
	v_mfma_f32_16x16x32_bf16 v[72:75], v[220:223], v[174:177], v[72:75]
	v_mfma_f32_16x16x32_bf16 v[68:71], v[206:209], v[182:185], v[68:71]
	v_mfma_f32_16x16x32_bf16 v[64:67], v[220:223], v[182:185], v[64:67]
	v_mfma_f32_16x16x32_bf16 v[112:115], v[216:219], v[148:151], v[112:115]
	v_mfma_f32_16x16x32_bf16 v[104:107], v[224:227], v[148:151], v[104:107]
	v_mfma_f32_16x16x32_bf16 v[96:99], v[216:219], v[170:173], v[96:99]
	v_mfma_f32_16x16x32_bf16 v[88:91], v[224:227], v[170:173], v[88:91]
	v_mfma_f32_16x16x32_bf16 v[80:83], v[216:219], v[178:181], v[80:83]
	v_mfma_f32_16x16x32_bf16 v[72:75], v[224:227], v[178:181], v[72:75]
	v_mfma_f32_16x16x32_bf16 v[68:71], v[216:219], v[186:189], v[68:71]
	v_mfma_f32_16x16x32_bf16 v[64:67], v[224:227], v[186:189], v[64:67]
	s_setprio 0
	s_mov_b32 m0, s88
	v_lshl_add_u64 v[232:233], s[2:3], 0, v[156:157]
	s_barrier
	ds_read_b128 v[144:147], v214 offset:16384
	ds_read_b128 v[148:151], v214 offset:17408
	ds_read_b128 v[152:155], v214 offset:18432
	ds_read_b128 v[170:173], v214 offset:19456
	ds_read_b128 v[174:177], v214 offset:20480
	ds_read_b128 v[178:181], v214 offset:21504
	ds_read_b128 v[182:185], v214 offset:22528
	ds_read_b128 v[186:189], v214 offset:23552
	global_load_lds_dwordx4 v[232:233], off
	v_lshl_add_u64 v[234:235], s[2:3], 0, v[162:163]
	s_mov_b32 m0, s89
	s_nop 0
	global_load_lds_dwordx4 v[234:235], off
	s_barrier
	s_waitcnt lgkmcnt(0)
	s_setprio 1
	s_waitcnt lgkmcnt(0)
	v_mfma_f32_16x16x32_bf16 v[60:63], v[128:131], v[144:147], v[60:63]
	v_mfma_f32_16x16x32_bf16 v[56:59], v[136:139], v[144:147], v[56:59]
	v_mfma_f32_16x16x32_bf16 v[52:55], v[128:131], v[152:155], v[52:55]
	v_mfma_f32_16x16x32_bf16 v[44:47], v[136:139], v[152:155], v[44:47]
	v_mfma_f32_16x16x32_bf16 v[36:39], v[128:131], v[174:177], v[36:39]
	v_mfma_f32_16x16x32_bf16 v[28:31], v[136:139], v[174:177], v[28:31]
	v_mfma_f32_16x16x32_bf16 v[20:23], v[128:131], v[182:185], v[20:23]
	v_mfma_f32_16x16x32_bf16 v[12:15], v[136:139], v[182:185], v[12:15]
	v_mfma_f32_16x16x32_bf16 v[60:63], v[132:135], v[148:151], v[60:63]
	v_mfma_f32_16x16x32_bf16 v[56:59], v[140:143], v[148:151], v[56:59]
	v_mfma_f32_16x16x32_bf16 v[52:55], v[132:135], v[170:173], v[52:55]
	v_mfma_f32_16x16x32_bf16 v[44:47], v[140:143], v[170:173], v[44:47]
	v_mfma_f32_16x16x32_bf16 v[36:39], v[132:135], v[178:181], v[36:39]
	v_mfma_f32_16x16x32_bf16 v[28:31], v[140:143], v[178:181], v[28:31]
	v_mfma_f32_16x16x32_bf16 v[20:23], v[132:135], v[186:189], v[20:23]
	v_mfma_f32_16x16x32_bf16 v[12:15], v[140:143], v[186:189], v[12:15]
	s_setprio 0
	s_barrier
	s_add_u32 s60, s60, s54
	s_addc_u32 s61, s61, 0
	s_add_i32 s21, s21, s53
	v_lshl_add_u64 v[236:237], s[60:61], 0, v[156:157]
	s_mov_b32 m0, s21
	v_lshl_add_u64 v[238:239], s[60:61], 0, v[162:163]
	global_load_lds_dwordx4 v[236:237], off
	s_add_i32 m0, s21, 0x2000
	s_nop 0
	global_load_lds_dwordx4 v[238:239], off
	s_waitcnt vmcnt(6)
	s_barrier
	s_setprio 1
	v_mfma_f32_16x16x32_bf16 v[48:51], v[206:209], v[144:147], v[48:51]
	v_mfma_f32_16x16x32_bf16 v[40:43], v[220:223], v[144:147], v[40:43]
	v_mfma_f32_16x16x32_bf16 v[32:35], v[206:209], v[152:155], v[32:35]
	v_mfma_f32_16x16x32_bf16 v[24:27], v[220:223], v[152:155], v[24:27]
	v_mfma_f32_16x16x32_bf16 v[16:19], v[206:209], v[174:177], v[16:19]
	v_mfma_f32_16x16x32_bf16 v[8:11], v[220:223], v[174:177], v[8:11]
	v_mfma_f32_16x16x32_bf16 v[4:7], v[206:209], v[182:185], v[4:7]
	v_mfma_f32_16x16x32_bf16 v[0:3], v[220:223], v[182:185], v[0:3]
	v_mfma_f32_16x16x32_bf16 v[48:51], v[216:219], v[148:151], v[48:51]
	v_mfma_f32_16x16x32_bf16 v[40:43], v[224:227], v[148:151], v[40:43]
	v_mfma_f32_16x16x32_bf16 v[32:35], v[216:219], v[170:173], v[32:35]
	v_mfma_f32_16x16x32_bf16 v[24:27], v[224:227], v[170:173], v[24:27]
	v_mfma_f32_16x16x32_bf16 v[16:19], v[216:219], v[178:181], v[16:19]
	v_mfma_f32_16x16x32_bf16 v[8:11], v[224:227], v[178:181], v[8:11]
	v_mfma_f32_16x16x32_bf16 v[4:7], v[216:219], v[186:189], v[4:7]
	v_mfma_f32_16x16x32_bf16 v[0:3], v[224:227], v[186:189], v[0:3]
	s_setprio 0
	s_add_i32 s21, 0, 0x18000
	v_add_u32_e32 v140, s21, v161
	s_barrier
	ds_read_b128 v[128:131], v140
	ds_read_b128 v[132:135], v140 offset:1024
	ds_read_b128 v[136:139], v140 offset:2048
	ds_read_b128 v[140:143], v140 offset:3072
	s_add_u32 s2, s2, s54
	s_addc_u32 s3, s3, 0
	s_mov_b32 m0, s94
	v_lshl_add_u64 v[206:207], s[2:3], 0, v[156:157]
	ds_read_b128 v[144:147], v214 offset:32768
	ds_read_b128 v[148:151], v214 offset:33792
	ds_read_b128 v[152:155], v214 offset:34816
	ds_read_b128 v[170:173], v214 offset:35840
	ds_read_b128 v[174:177], v214 offset:36864
	ds_read_b128 v[178:181], v214 offset:37888
	ds_read_b128 v[182:185], v214 offset:38912
	ds_read_b128 v[186:189], v214 offset:39936
	global_load_lds_dwordx4 v[206:207], off
	v_lshl_add_u64 v[206:207], s[2:3], 0, v[162:163]
	s_mov_b32 m0, s95
	s_nop 0
	global_load_lds_dwordx4 v[206:207], off
	s_waitcnt lgkmcnt(8)
	s_barrier
	s_waitcnt lgkmcnt(0)
	s_setprio 1
	s_waitcnt lgkmcnt(0)
	v_mfma_f32_16x16x32_bf16 v[124:127], v[128:131], v[144:147], v[124:127]
	v_mfma_f32_16x16x32_bf16 v[120:123], v[136:139], v[144:147], v[120:123]
	v_mfma_f32_16x16x32_bf16 v[116:119], v[128:131], v[152:155], v[116:119]
	v_mfma_f32_16x16x32_bf16 v[108:111], v[136:139], v[152:155], v[108:111]
	v_mfma_f32_16x16x32_bf16 v[100:103], v[128:131], v[174:177], v[100:103]
	v_mfma_f32_16x16x32_bf16 v[92:95], v[136:139], v[174:177], v[92:95]
	v_mfma_f32_16x16x32_bf16 v[84:87], v[128:131], v[182:185], v[84:87]
	v_mfma_f32_16x16x32_bf16 v[76:79], v[136:139], v[182:185], v[76:79]
	v_mfma_f32_16x16x32_bf16 v[124:127], v[132:135], v[148:151], v[124:127]
	v_mfma_f32_16x16x32_bf16 v[120:123], v[140:143], v[148:151], v[120:123]
	v_mfma_f32_16x16x32_bf16 v[116:119], v[132:135], v[170:173], v[116:119]
	v_mfma_f32_16x16x32_bf16 v[108:111], v[140:143], v[170:173], v[108:111]
	v_mfma_f32_16x16x32_bf16 v[100:103], v[132:135], v[178:181], v[100:103]
	v_mfma_f32_16x16x32_bf16 v[92:95], v[140:143], v[178:181], v[92:95]
	v_mfma_f32_16x16x32_bf16 v[84:87], v[132:135], v[186:189], v[84:87]
	v_mfma_f32_16x16x32_bf16 v[76:79], v[140:143], v[186:189], v[76:79]
	s_setprio 0
	s_barrier
	s_add_i32 s2, 0, 0x1c000
	s_add_i32 s3, s21, s53
	v_add_u32_e32 v215, s2, v161
	v_lshl_add_u64 v[228:229], v[228:229], 0, s[50:51]
	s_mov_b32 m0, s3
	ds_read_b128 v[206:209], v215
	ds_read_b128 v[216:219], v215 offset:1024
	ds_read_b128 v[220:223], v215 offset:2048
	ds_read_b128 v[224:227], v215 offset:3072
	global_load_lds_dwordx4 v[228:229], off
	v_lshl_add_u64 v[228:229], v[230:231], 0, s[50:51]
	s_add_i32 m0, s3, 0x2000
	s_nop 0
	global_load_lds_dwordx4 v[228:229], off
	s_barrier
	s_waitcnt lgkmcnt(0)
	s_setprio 1
	s_waitcnt lgkmcnt(0)
	v_mfma_f32_16x16x32_bf16 v[112:115], v[206:209], v[144:147], v[112:115]
	v_mfma_f32_16x16x32_bf16 v[104:107], v[220:223], v[144:147], v[104:107]
	v_mfma_f32_16x16x32_bf16 v[96:99], v[206:209], v[152:155], v[96:99]
	v_mfma_f32_16x16x32_bf16 v[88:91], v[220:223], v[152:155], v[88:91]
	v_mfma_f32_16x16x32_bf16 v[80:83], v[206:209], v[174:177], v[80:83]
	v_mfma_f32_16x16x32_bf16 v[72:75], v[220:223], v[174:177], v[72:75]
	v_mfma_f32_16x16x32_bf16 v[68:71], v[206:209], v[182:185], v[68:71]
	v_mfma_f32_16x16x32_bf16 v[64:67], v[220:223], v[182:185], v[64:67]
	v_mfma_f32_16x16x32_bf16 v[112:115], v[216:219], v[148:151], v[112:115]
	v_mfma_f32_16x16x32_bf16 v[104:107], v[224:227], v[148:151], v[104:107]
	v_mfma_f32_16x16x32_bf16 v[96:99], v[216:219], v[170:173], v[96:99]
	v_mfma_f32_16x16x32_bf16 v[88:91], v[224:227], v[170:173], v[88:91]
	v_mfma_f32_16x16x32_bf16 v[80:83], v[216:219], v[178:181], v[80:83]
	v_mfma_f32_16x16x32_bf16 v[72:75], v[224:227], v[178:181], v[72:75]
	v_mfma_f32_16x16x32_bf16 v[68:71], v[216:219], v[186:189], v[68:71]
	v_mfma_f32_16x16x32_bf16 v[64:67], v[224:227], v[186:189], v[64:67]
	s_setprio 0
	s_mov_b32 m0, s96
	v_lshl_add_u64 v[228:229], v[232:233], 0, s[50:51]
	s_barrier
	ds_read_b128 v[144:147], v214 offset:49152
	ds_read_b128 v[148:151], v214 offset:50176
	ds_read_b128 v[152:155], v214 offset:51200
	ds_read_b128 v[170:173], v214 offset:52224
	ds_read_b128 v[174:177], v214 offset:53248
	ds_read_b128 v[178:181], v214 offset:54272
	ds_read_b128 v[182:185], v214 offset:55296
	ds_read_b128 v[186:189], v214 offset:56320
	global_load_lds_dwordx4 v[228:229], off
	v_lshl_add_u64 v[228:229], v[234:235], 0, s[50:51]
	s_mov_b32 m0, s97
	s_nop 0
	global_load_lds_dwordx4 v[228:229], off
	s_barrier
	s_waitcnt lgkmcnt(0)
	s_setprio 1
	s_waitcnt lgkmcnt(0)
	v_mfma_f32_16x16x32_bf16 v[60:63], v[128:131], v[144:147], v[60:63]
	v_mfma_f32_16x16x32_bf16 v[56:59], v[136:139], v[144:147], v[56:59]
	v_mfma_f32_16x16x32_bf16 v[52:55], v[128:131], v[152:155], v[52:55]
	v_mfma_f32_16x16x32_bf16 v[44:47], v[136:139], v[152:155], v[44:47]
	v_mfma_f32_16x16x32_bf16 v[36:39], v[128:131], v[174:177], v[36:39]
	v_mfma_f32_16x16x32_bf16 v[28:31], v[136:139], v[174:177], v[28:31]
	v_mfma_f32_16x16x32_bf16 v[20:23], v[128:131], v[182:185], v[20:23]
	v_mfma_f32_16x16x32_bf16 v[12:15], v[136:139], v[182:185], v[12:15]
	v_mfma_f32_16x16x32_bf16 v[60:63], v[132:135], v[148:151], v[60:63]
	v_mfma_f32_16x16x32_bf16 v[56:59], v[140:143], v[148:151], v[56:59]
	v_mfma_f32_16x16x32_bf16 v[52:55], v[132:135], v[170:173], v[52:55]
	v_mfma_f32_16x16x32_bf16 v[44:47], v[140:143], v[170:173], v[44:47]
	v_mfma_f32_16x16x32_bf16 v[36:39], v[132:135], v[178:181], v[36:39]
	v_mfma_f32_16x16x32_bf16 v[28:31], v[140:143], v[178:181], v[28:31]
	v_mfma_f32_16x16x32_bf16 v[20:23], v[132:135], v[186:189], v[20:23]
	v_mfma_f32_16x16x32_bf16 v[12:15], v[140:143], v[186:189], v[12:15]
	s_setprio 0
	s_barrier
	s_add_i32 s2, s2, s53
	v_lshl_add_u64 v[128:129], v[236:237], 0, s[50:51]
	s_mov_b32 m0, s2
	s_nop 0
	global_load_lds_dwordx4 v[128:129], off
	v_lshl_add_u64 v[128:129], v[238:239], 0, s[50:51]
	s_add_i32 m0, s2, 0x2000
	s_nop 0
	global_load_lds_dwordx4 v[128:129], off
	s_waitcnt vmcnt(6)
	s_barrier
	s_setprio 1
	v_mfma_f32_16x16x32_bf16 v[48:51], v[206:209], v[144:147], v[48:51]
	v_mfma_f32_16x16x32_bf16 v[40:43], v[220:223], v[144:147], v[40:43]
	v_mfma_f32_16x16x32_bf16 v[32:35], v[206:209], v[152:155], v[32:35]
	v_mfma_f32_16x16x32_bf16 v[24:27], v[220:223], v[152:155], v[24:27]
	v_mfma_f32_16x16x32_bf16 v[16:19], v[206:209], v[174:177], v[16:19]
	v_mfma_f32_16x16x32_bf16 v[8:11], v[220:223], v[174:177], v[8:11]
	v_mfma_f32_16x16x32_bf16 v[4:7], v[206:209], v[182:185], v[4:7]
	v_mfma_f32_16x16x32_bf16 v[0:3], v[220:223], v[182:185], v[0:3]
	v_mfma_f32_16x16x32_bf16 v[48:51], v[216:219], v[148:151], v[48:51]
	v_mfma_f32_16x16x32_bf16 v[40:43], v[224:227], v[148:151], v[40:43]
	v_mfma_f32_16x16x32_bf16 v[32:35], v[216:219], v[170:173], v[32:35]
	v_mfma_f32_16x16x32_bf16 v[24:27], v[224:227], v[170:173], v[24:27]
	v_mfma_f32_16x16x32_bf16 v[16:19], v[216:219], v[178:181], v[16:19]
	v_mfma_f32_16x16x32_bf16 v[8:11], v[224:227], v[178:181], v[8:11]
	v_mfma_f32_16x16x32_bf16 v[4:7], v[216:219], v[186:189], v[4:7]
	v_mfma_f32_16x16x32_bf16 v[0:3], v[224:227], v[186:189], v[0:3]
	s_setprio 0
	s_add_u32 s83, s83, 0x100
	s_addc_u32 vcc_lo, vcc_lo, 0
	s_add_u32 s6, s6, 0x100
	s_addc_u32 s7, s7, 0
	s_cmp_ge_u32 vcc_hi, s84
	s_mov_b32 s2, vcc_hi
	s_barrier
	s_cbranch_scc0 .LBB0_514
	s_min_i32 s2, s85, 0x80
	s_ashr_i32 s2, s2, 4
	s_lshl_b32 s84, s85, 8
	s_mul_hi_i32 s3, s2, 0x9000
	s_mul_i32 s2, s2, 0x9000
	s_add_u32 s2, s42, s2
	v_lshl_or_b32 v144, s24, 8, v213
	s_addc_u32 s3, s43, s3
	v_ashrrev_i32_e32 v145, 31, v144
	v_lshl_add_u64 v[140:141], v[144:145], 2, s[2:3]
	global_load_dwordx4 v[128:131], v[140:141], off
	global_load_dwordx4 v[132:135], v[140:141], off offset:64
	global_load_dwordx4 v[136:139], v[140:141], off offset:512
	s_nop 0
	global_load_dwordx4 v[140:143], v[140:141], off offset:576
	v_lshl_add_u64 v[170:171], v[164:165], 0, v[144:145]
	s_cmpk_lt_i32 s85, 0x80
	s_mov_b64 s[2:3], -1
	s_cbranch_scc1 .Lres_lat
	s_waitcnt vmcnt(0)
	v_pk_mul_f32 v[184:185], s[68:69], v[130:131]
	v_pk_mul_f32 v[186:187], s[46:47], v[128:129]
	v_pk_mul_f32 v[180:181], s[68:69], v[134:135]
	v_pk_mul_f32 v[182:183], s[46:47], v[132:133]
	v_pk_mul_f32 v[176:177], s[68:69], v[138:139]
	v_pk_mul_f32 v[178:179], s[46:47], v[136:137]
	v_pk_mul_f32 v[172:173], s[68:69], v[142:143]
	v_pk_mul_f32 v[174:175], s[46:47], v[140:141]
	s_branch .LBB0_517
.Lres_lat:
	s_ashr_i32 s85, s84, 31
	s_lshl_b64 s[2:3], s[84:85], 12
	s_add_u32 s82, s66, s2
	s_addc_u32 s83, s67, s3
	s_add_u32 s2, s62, s2
	s_addc_u32 s3, s63, s3
	s_mov_b64 s[6:7], s[82:83]
	v_lshlrev_b32_e32 v189, 2, v170
	global_load_dwordx4 v[144:147], v189, s[2:3]
	global_load_dwordx4 v[148:151], v189, s[2:3] offset:64
	global_load_dwordx4 v[152:155], v189, s[2:3] offset:512
	global_load_dwordx4 v[206:209], v189, s[2:3] offset:576
	s_add_u32 s2, s2, 0x10000
	s_addc_u32 s3, s3, 0
	global_load_dwordx4 v[216:219], v189, s[2:3]
	global_load_dwordx4 v[220:223], v189, s[2:3] offset:64
	global_load_dwordx4 v[224:227], v189, s[2:3] offset:512
	global_load_dwordx4 v[228:231], v189, s[2:3] offset:576
	s_add_u32 s2, s2, 0x10000
	s_addc_u32 s3, s3, 0
	global_load_dwordx4 v[232:235], v189, s[2:3]
	global_load_dwordx4 v[236:239], v189, s[2:3] offset:64
	global_load_dwordx4 v[240:243], v189, s[2:3] offset:512
	global_load_dwordx4 v[244:247], v189, s[2:3] offset:576
	s_add_u32 s2, s2, 0x10000
	s_addc_u32 s3, s3, 0
	global_load_dwordx4 v[248:251], v189, s[2:3]
	s_waitcnt vmcnt(13)
	v_pk_mul_f32 v[184:185], s[68:69], v[130:131]
	v_pk_mul_f32 v[186:187], s[46:47], v[128:129]
	v_pk_mul_f32 v[180:181], s[68:69], v[134:135]
	v_pk_mul_f32 v[182:183], s[46:47], v[132:133]
	v_pk_mul_f32 v[176:177], s[68:69], v[138:139]
	v_pk_mul_f32 v[178:179], s[46:47], v[136:137]
	v_pk_mul_f32 v[172:173], s[68:69], v[142:143]
	v_pk_mul_f32 v[174:175], s[46:47], v[140:141]
	global_load_dwordx4 v[132:135], v189, s[2:3] offset:64
	global_load_dwordx4 v[136:139], v189, s[2:3] offset:512
	global_load_dwordx4 v[140:143], v189, s[2:3] offset:576
	s_add_u32 s2, s2, 0x50000
	s_addc_u32 s3, s3, 0
	s_waitcnt vmcnt(15)
	v_pk_fma_f32 v[146:147], v[126:127], v[184:185], v[146:147]
	v_pk_fma_f32 v[144:145], v[124:125], v[186:187], v[144:145]
	global_store_dwordx4 v189, v[144:147], s[6:7]
	s_nop 0
	global_load_dwordx4 v[144:147], v189, s[2:3]
	s_waitcnt vmcnt(16)
	v_pk_fma_f32 v[150:151], v[122:123], v[180:181], v[150:151]
	v_pk_fma_f32 v[148:149], v[120:121], v[182:183], v[148:149]
	global_store_dwordx4 v189, v[148:151], s[6:7] offset:64
	s_nop 0
	global_load_dwordx4 v[148:151], v189, s[2:3] offset:64
	s_waitcnt vmcnt(17)
	v_pk_fma_f32 v[154:155], v[114:115], v[176:177], v[154:155]
	v_pk_fma_f32 v[152:153], v[112:113], v[178:179], v[152:153]
	global_store_dwordx4 v189, v[152:155], s[6:7] offset:512
	s_nop 0
	global_load_dwordx4 v[152:155], v189, s[2:3] offset:512
	s_waitcnt vmcnt(18)
	v_pk_fma_f32 v[208:209], v[106:107], v[172:173], v[208:209]
	v_pk_fma_f32 v[206:207], v[104:105], v[174:175], v[206:207]
	global_store_dwordx4 v189, v[206:209], s[6:7] offset:576
	s_add_u32 s6, s6, 0x10000
	s_addc_u32 s7, s7, 0
	global_load_dwordx4 v[206:209], v189, s[2:3] offset:576
	s_add_u32 s2, s2, 0x10000
	s_addc_u32 s3, s3, 0
	s_waitcnt vmcnt(19)
	v_pk_fma_f32 v[218:219], v[118:119], v[184:185], v[218:219]
	v_pk_fma_f32 v[216:217], v[116:117], v[186:187], v[216:217]
	global_store_dwordx4 v189, v[216:219], s[6:7]
	s_nop 0
	global_load_dwordx4 v[216:219], v189, s[2:3]
	s_waitcnt vmcnt(20)
	v_pk_fma_f32 v[222:223], v[110:111], v[180:181], v[222:223]
	v_pk_fma_f32 v[220:221], v[108:109], v[182:183], v[220:221]
	global_store_dwordx4 v189, v[220:223], s[6:7] offset:64
	s_nop 0
	global_load_dwordx4 v[220:223], v189, s[2:3] offset:64
	s_waitcnt vmcnt(21)
	v_pk_fma_f32 v[226:227], v[98:99], v[176:177], v[226:227]
	v_pk_fma_f32 v[224:225], v[96:97], v[178:179], v[224:225]
	global_store_dwordx4 v189, v[224:227], s[6:7] offset:512
	s_nop 0
	global_load_dwordx4 v[224:227], v189, s[2:3] offset:512
	s_waitcnt vmcnt(22)
	v_pk_fma_f32 v[230:231], v[90:91], v[172:173], v[230:231]
	v_pk_fma_f32 v[228:229], v[88:89], v[174:175], v[228:229]
	global_store_dwordx4 v189, v[228:231], s[6:7] offset:576
	s_add_u32 s6, s6, 0x10000
	s_addc_u32 s7, s7, 0
	global_load_dwordx4 v[228:231], v189, s[2:3] offset:576
	s_add_u32 s2, s2, 0x10000
	s_addc_u32 s3, s3, 0
	s_waitcnt vmcnt(23)
	v_pk_fma_f32 v[234:235], v[102:103], v[184:185], v[234:235]
	v_pk_fma_f32 v[232:233], v[100:101], v[186:187], v[232:233]
	global_store_dwordx4 v189, v[232:235], s[6:7]
	s_nop 0
	global_load_dwordx4 v[232:235], v189, s[2:3]
	s_waitcnt vmcnt(24)
	v_pk_fma_f32 v[238:239], v[94:95], v[180:181], v[238:239]
	v_pk_fma_f32 v[236:237], v[92:93], v[182:183], v[236:237]
	global_store_dwordx4 v189, v[236:239], s[6:7] offset:64
	s_nop 0
	global_load_dwordx4 v[236:239], v189, s[2:3] offset:64
	s_waitcnt vmcnt(25)
	v_pk_fma_f32 v[242:243], v[82:83], v[176:177], v[242:243]
	v_pk_fma_f32 v[240:241], v[80:81], v[178:179], v[240:241]
	global_store_dwordx4 v189, v[240:243], s[6:7] offset:512
	s_nop 0
	global_load_dwordx4 v[240:243], v189, s[2:3] offset:512
	s_waitcnt vmcnt(26)
	v_pk_fma_f32 v[246:247], v[74:75], v[172:173], v[246:247]
	v_pk_fma_f32 v[244:245], v[72:73], v[174:175], v[244:245]
	global_store_dwordx4 v189, v[244:247], s[6:7] offset:576
	s_add_u32 s6, s6, 0x10000
	s_addc_u32 s7, s7, 0
	global_load_dwordx4 v[244:247], v189, s[2:3] offset:576
	s_add_u32 s2, s2, 0x10000
	s_addc_u32 s3, s3, 0
	s_waitcnt vmcnt(27)
	v_pk_fma_f32 v[250:251], v[86:87], v[184:185], v[250:251]
	v_pk_fma_f32 v[248:249], v[84:85], v[186:187], v[248:249]
	global_store_dwordx4 v189, v[248:251], s[6:7]
	s_nop 0
	global_load_dwordx4 v[248:251], v189, s[2:3]
	s_waitcnt vmcnt(28)
	v_pk_fma_f32 v[134:135], v[78:79], v[180:181], v[134:135]
	v_pk_fma_f32 v[132:133], v[76:77], v[182:183], v[132:133]
	global_store_dwordx4 v189, v[132:135], s[6:7] offset:64
	s_nop 0
	global_load_dwordx4 v[132:135], v189, s[2:3] offset:64
	s_waitcnt vmcnt(29)
	v_pk_fma_f32 v[138:139], v[70:71], v[176:177], v[138:139]
	v_pk_fma_f32 v[136:137], v[68:69], v[178:179], v[136:137]
	global_store_dwordx4 v189, v[136:139], s[6:7] offset:512
	s_nop 0
	global_load_dwordx4 v[136:139], v189, s[2:3] offset:512
	s_waitcnt vmcnt(30)
	v_pk_fma_f32 v[142:143], v[66:67], v[172:173], v[142:143]
	v_pk_fma_f32 v[140:141], v[64:65], v[174:175], v[140:141]
	global_store_dwordx4 v189, v[140:143], s[6:7] offset:576
	s_add_u32 s6, s6, 0x50000
	s_addc_u32 s7, s7, 0
	global_load_dwordx4 v[128:131], v189, s[2:3] offset:576
	s_waitcnt vmcnt(30)
	v_pk_fma_f32 v[146:147], v[62:63], v[184:185], v[146:147]
	v_pk_fma_f32 v[144:145], v[60:61], v[186:187], v[144:145]
	global_store_dwordx4 v189, v[144:147], s[6:7]
	s_nop 0
	s_waitcnt vmcnt(29)
	v_pk_fma_f32 v[150:151], v[58:59], v[180:181], v[150:151]
	v_pk_fma_f32 v[148:149], v[56:57], v[182:183], v[148:149]
	global_store_dwordx4 v189, v[148:151], s[6:7] offset:64
	s_nop 0
	s_waitcnt vmcnt(28)
	v_pk_fma_f32 v[154:155], v[50:51], v[176:177], v[154:155]
	v_pk_fma_f32 v[152:153], v[48:49], v[178:179], v[152:153]
	global_store_dwordx4 v189, v[152:155], s[6:7] offset:512
	s_nop 0
	s_waitcnt vmcnt(27)
	v_pk_fma_f32 v[208:209], v[42:43], v[172:173], v[208:209]
	v_pk_fma_f32 v[206:207], v[40:41], v[174:175], v[206:207]
	global_store_dwordx4 v189, v[206:209], s[6:7] offset:576
	s_add_u32 s6, s6, 0x10000
	s_addc_u32 s7, s7, 0
	s_waitcnt vmcnt(26)
	v_pk_fma_f32 v[218:219], v[54:55], v[184:185], v[218:219]
	v_pk_fma_f32 v[216:217], v[52:53], v[186:187], v[216:217]
	global_store_dwordx4 v189, v[216:219], s[6:7]
	s_nop 0
	s_waitcnt vmcnt(25)
	v_pk_fma_f32 v[222:223], v[46:47], v[180:181], v[222:223]
	v_pk_fma_f32 v[220:221], v[44:45], v[182:183], v[220:221]
	global_store_dwordx4 v189, v[220:223], s[6:7] offset:64
	s_nop 0
	s_waitcnt vmcnt(24)
	v_pk_fma_f32 v[226:227], v[34:35], v[176:177], v[226:227]
	v_pk_fma_f32 v[224:225], v[32:33], v[178:179], v[224:225]
	global_store_dwordx4 v189, v[224:227], s[6:7] offset:512
	s_nop 0
	s_waitcnt vmcnt(23)
	v_pk_fma_f32 v[230:231], v[26:27], v[172:173], v[230:231]
	v_pk_fma_f32 v[228:229], v[24:25], v[174:175], v[228:229]
	global_store_dwordx4 v189, v[228:231], s[6:7] offset:576
	s_add_u32 s6, s6, 0x10000
	s_addc_u32 s7, s7, 0
	s_waitcnt vmcnt(22)
	v_pk_fma_f32 v[234:235], v[38:39], v[184:185], v[234:235]
	v_pk_fma_f32 v[232:233], v[36:37], v[186:187], v[232:233]
	global_store_dwordx4 v189, v[232:235], s[6:7]
	s_nop 0
	s_waitcnt vmcnt(21)
	v_pk_fma_f32 v[238:239], v[30:31], v[180:181], v[238:239]
	v_pk_fma_f32 v[236:237], v[28:29], v[182:183], v[236:237]
	global_store_dwordx4 v189, v[236:239], s[6:7] offset:64
	s_nop 0
	s_waitcnt vmcnt(20)
	v_pk_fma_f32 v[242:243], v[18:19], v[176:177], v[242:243]
	v_pk_fma_f32 v[240:241], v[16:17], v[178:179], v[240:241]
	global_store_dwordx4 v189, v[240:243], s[6:7] offset:512
	s_nop 0
	s_waitcnt vmcnt(19)
	v_pk_fma_f32 v[246:247], v[10:11], v[172:173], v[246:247]
	v_pk_fma_f32 v[244:245], v[8:9], v[174:175], v[244:245]
	global_store_dwordx4 v189, v[244:247], s[6:7] offset:576
	s_add_u32 s6, s6, 0x10000
	s_addc_u32 s7, s7, 0
	s_waitcnt vmcnt(18)
	v_pk_fma_f32 v[250:251], v[22:23], v[184:185], v[250:251]
	v_pk_fma_f32 v[248:249], v[20:21], v[186:187], v[248:249]
	global_store_dwordx4 v189, v[248:251], s[6:7]
	s_nop 0
	s_waitcnt vmcnt(17)
	v_pk_fma_f32 v[134:135], v[14:15], v[180:181], v[134:135]
	v_pk_fma_f32 v[132:133], v[12:13], v[182:183], v[132:133]
	global_store_dwordx4 v189, v[132:135], s[6:7] offset:64
	s_nop 0
	s_waitcnt vmcnt(16)
	v_pk_fma_f32 v[138:139], v[6:7], v[176:177], v[138:139]
	v_pk_fma_f32 v[136:137], v[4:5], v[178:179], v[136:137]
	global_store_dwordx4 v189, v[136:139], s[6:7] offset:512
	s_nop 0
	s_waitcnt vmcnt(15)
	v_pk_fma_f32 v[130:131], v[2:3], v[172:173], v[130:131]
	v_pk_fma_f32 v[128:129], v[0:1], v[174:175], v[128:129]
	s_mov_b64 s[2:3], 0
